# S17 plus the remaining 3 gate quads issued at the end of QK of the last masked iteration (into dead Q-fragment registers), so all 8 gate loads precede the final PV
# speedup vs baseline: 1.0079x; 1.0003x over previous
; __device__ __forceinline__ unsigned cvt_pk_bf16(float lo, float hi) { unsigned r; asm volatile("v_cvt_pk_bf16_f32 %0, %1, %2" : "=v"(r) : "v"(lo), "v"(hi)); return r; }
; __device__ __forceinline__ float bf_lo(unsigned w) { return __uint_as_float(w << 16); }
; __device__ __forceinline__ float bf_hi(unsigned w) { return __uint_as_float(w & 0xffff0000u); }
; __device__ __forceinline__ void unit(LAS unsigned char* lds, int b, int h, int qb, const bf16_t* Q, const bf16_t* Kn, const bf16_t* Kr, const bf16_t* VT, const bf16_t* proj, bf16_t* ymix, int wv) {
;     ...
;     lrun += shfl_xor_f(lrun, 32);
;     const float inv = 1.f / lrun;
;     const size_t tok = (size_t)tok0 + qidx;
;     u32x2 gts[4][4];
; #pragma unroll
;     for (int blk = 0; blk < 4; ++blk)
; #pragma unroll
;         for (int g = 0; g < 4; ++g) gts[blk][g] = *(const u32x2*)(proj + tok * NIN + PJ_BG + h * 128 + 32 * blk + 8 * g + 4 * hi);
; #pragma unroll
;     for (int blk = 0; blk < 4; ++blk)
; #pragma unroll
;         for (int g = 0; g < 4; ++g) { const int dv = 32 * blk + 8 * g + 4 * hi; const u32x2 gt = gts[blk][g];
;             u32x2 w; w.x = cvt_pk_bf16(o[blk][4 * g + 0] * inv * bf_lo(gt.x), o[blk][4 * g + 1] * inv * bf_hi(gt.x)); w.y = cvt_pk_bf16(o[blk][4 * g + 2] * inv * bf_lo(gt.y), o[blk][4 * g + 3] * inv * bf_hi(gt.y));
;             *(u32x2*)(ymix + tok * DM + 512 + h * 128 + dv) = w; }
.LBB0_605:
	s_add_i32 s8, s71, 0
	s_add_i32 s8, s8, 0x12c00
	v_add3_u32 v0, s8, v227, v226
	ds_read2_b64 v[2:5], v0 offset1:2
	v_ashrrev_i32_e32 v217, 31, v216
	v_mov_b64_e32 v[6:7], s[22:23]
	v_lshl_add_u64 v[120:121], v[216:217], 0, s[54:55]
	v_mad_u64_u32 v[122:123], s[8:9], v120, s66, v[6:7]
	ds_read2_b64 v[6:9], v0 offset0:4 offset1:6
	ds_read2_b64 v[12:15], v0 offset0:8 offset1:10
	v_add_u32_e32 v88, 0x1000, v0
	v_add_u32_e32 v104, 0x2000, v0
	s_waitcnt lgkmcnt(2)
	v_mfma_f32_32x32x16_bf16 v[64:79], v[2:5], v[200:203], v[64:79]
	ds_read2_b64 v[2:5], v0 offset0:12 offset1:14
	v_add_u32_e32 v0, 0x3000, v0
	v_mad_i32_i24 v123, v121, s66, v123
	s_lshl_b32 s12, s69, 1
	ds_read2_b64 v[80:83], v88 offset0:32 offset1:34
	ds_read2_b64 v[84:87], v88 offset0:36 offset1:38
	v_mov_b32_e32 v11, v222
	s_add_i32 s68, s68, s31
	s_waitcnt lgkmcnt(4)
	v_mfma_f32_32x32x16_bf16 v[64:79], v[6:9], v[196:199], v[64:79]
	ds_read2_b64 v[6:9], v88 offset0:40 offset1:42
	ds_read2_b64 v[88:91], v88 offset0:44 offset1:46
	ds_read2_b64 v[92:95], v104 offset0:64 offset1:66
	ds_read2_b64 v[96:99], v104 offset0:68 offset1:70
	ds_read2_b64 v[100:103], v104 offset0:72 offset1:74
	ds_read2_b64 v[104:107], v104 offset0:76 offset1:78
	ds_read2_b64 v[108:111], v0 offset0:96 offset1:98
	s_cmpk_lt_i32 s68, 0x400
	s_waitcnt lgkmcnt(10)
	v_mfma_f32_32x32x16_bf16 v[64:79], v[12:15], v[192:195], v[64:79]
	ds_read2_b64 v[12:15], v0 offset0:100 offset1:102
	ds_read2_b64 v[112:115], v0 offset0:104 offset1:106
	ds_read2_b64 v[116:119], v0 offset0:108 offset1:110
	v_lshlrev_b32_e32 v0, 1, v225
	s_waitcnt lgkmcnt(0)
	s_barrier
	v_mfma_f32_32x32x16_bf16 v[64:79], v[2:5], v[180:183], v[64:79]
	v_lshl_add_u64 v[2:3], v[122:123], 0, s[12:13]
	v_lshl_add_u64 v[2:3], v[2:3], 0, v[0:1]
	v_add_co_u32_e32 v4, vcc, s67, v2
	s_nop 1
	v_addc_co_u32_e32 v5, vcc, 0, v3, vcc
	v_and_b32_e32 v168, 32, v222
	v_lshrrev_b32_e32 v168, 2, v168
	v_mov_b32_e32 v169, 0
	v_lshl_add_u64 v[168:169], v[4:5], 0, v[168:169]
	v_lshl_add_u64 v[2:3], v[2:3], 0, s[16:17]
	v_mfma_f32_32x32x16_bf16 v[48:63], v[80:83], v[200:203], v[48:63]
	v_lshlrev_b32_e32 v4, 2, v11
	v_xor_b32_e32 v4, 0x80, v4
	ds_bpermute_b32 v4, v4, v10
	v_mfma_f32_32x32x16_bf16 v[48:63], v[84:87], v[196:199], v[48:63]
	v_mfma_f32_32x32x16_bf16 v[48:63], v[6:9], v[192:195], v[48:63]
	s_waitcnt lgkmcnt(0)
	v_add_f32_e32 v6, v10, v4
	v_div_scale_f32 v7, s[8:9], v6, v6, 1.0
	v_rcp_f32_e32 v134, v7
	v_mfma_f32_32x32x16_bf16 v[48:63], v[88:91], v[180:183], v[48:63]
	s_nop 0
	v_mfma_f32_32x32x16_bf16 v[32:47], v[92:95], v[200:203], v[32:47]
	v_fma_f32 v92, -v7, v134, 1.0
	v_fmac_f32_e32 v134, v92, v134
	v_div_scale_f32 v92, vcc, 1.0, v6, 1.0
	v_mul_f32_e32 v93, v92, v134
	v_fma_f32 v94, -v7, v93, v92
	v_fmac_f32_e32 v93, v94, v134
	v_fma_f32 v7, -v7, v93, v92
	v_mfma_f32_32x32x16_bf16 v[16:31], v[108:111], v[200:203], v[16:31]
	v_div_fmas_f32 v7, v7, v134, v93
	v_div_fixup_f32 v92, v7, v6, 1.0
	v_mul_f32_e32 v64, v64, v92
	v_lshlrev_b64 v[6:7], 12, v[120:121]
	v_mul_f32_e32 v65, v65, v92
	v_lshl_add_u64 v[6:7], s[46:47], 0, v[6:7]
	v_lshl_add_u64 v[6:7], v[6:7], 0, s[12:13]
	v_lshl_add_u64 v[6:7], v[6:7], 0, v[0:1]
	v_mul_f32_e32 v0, v68, v92
	v_mfma_f32_32x32x16_bf16 v[16:31], v[12:15], v[196:199], v[16:31]
	v_mul_f32_e32 v12, v69, v92
	s_waitcnt vmcnt(3)
	v_permlane32_swap_b32_e32 v176, v178
	v_permlane32_swap_b32_e32 v177, v179
	v_lshlrev_b32_e32 v93, 16, v176
	v_mul_f32_e32 v64, v64, v93
	v_and_b32_e32 v93, 0xffff0000, v176
	v_mul_f32_e32 v65, v65, v93
	v_cvt_pk_bf16_f32 v136, v64, v65
	v_mul_f32_e32 v65, v66, v92
	v_lshlrev_b32_e32 v66, 16, v177
	v_mul_f32_e32 v65, v65, v66
	v_mul_f32_e32 v66, v67, v92
	v_and_b32_e32 v67, 0xffff0000, v177
	v_mul_f32_e32 v66, v66, v67
	v_cvt_pk_bf16_f32 v137, v65, v66
	v_and_b32_e32 v252, 32, v222
	v_lshrrev_b32_e32 v252, 2, v252
	v_mov_b32_e32 v253, 0
	v_lshl_add_u64 v[252:253], v[6:7], 0, v[252:253]
	s_waitcnt vmcnt(3)
	v_lshlrev_b32_e32 v64, 16, v178
	v_and_b32_e32 v13, 0xffff0000, v178
	v_mul_f32_e32 v0, v0, v64
	v_mul_f32_e32 v12, v12, v13
	v_cvt_pk_bf16_f32 v138, v0, v12
	v_mul_f32_e32 v0, v70, v92
	v_lshlrev_b32_e32 v13, 16, v179
	v_mul_f32_e32 v0, v0, v13
	v_mul_f32_e32 v13, v71, v92
	v_and_b32_e32 v14, 0xffff0000, v179
	v_mul_f32_e32 v13, v13, v14
	v_cvt_pk_bf16_f32 v139, v0, v13
	s_nop 1
	v_permlane32_swap_b32_e32 v136, v138
	v_permlane32_swap_b32_e32 v137, v139
	global_store_dwordx4 v[252:253], v[136:139], off offset:1024
	v_mul_f32_e32 v0, v72, v92
	s_waitcnt vmcnt(4)
	v_permlane32_swap_b32_e32 v184, v186
	v_permlane32_swap_b32_e32 v185, v187
	v_lshlrev_b32_e32 v12, 16, v184
	v_mul_f32_e32 v0, v0, v12
	v_mul_f32_e32 v12, v73, v92
	v_and_b32_e32 v13, 0xffff0000, v184
	v_mul_f32_e32 v12, v12, v13
	v_cvt_pk_bf16_f32 v140, v0, v12
	v_mul_f32_e32 v0, v74, v92
	v_lshlrev_b32_e32 v13, 16, v185
	v_mul_f32_e32 v0, v0, v13
	v_mul_f32_e32 v13, v75, v92
	v_and_b32_e32 v14, 0xffff0000, v185
	v_mul_f32_e32 v13, v13, v14
	v_cvt_pk_bf16_f32 v141, v0, v13
	v_mul_f32_e32 v0, v76, v92
	s_waitcnt vmcnt(4)
	v_lshlrev_b32_e32 v12, 16, v186
	v_mul_f32_e32 v0, v0, v12
	v_mul_f32_e32 v12, v77, v92
	v_and_b32_e32 v10, 0xffff0000, v186
	v_mul_f32_e32 v10, v12, v10
	v_cvt_pk_bf16_f32 v142, v0, v10
	v_mul_f32_e32 v0, v78, v92
	v_lshlrev_b32_e32 v12, 16, v187
	v_mul_f32_e32 v0, v0, v12
	v_mul_f32_e32 v12, v79, v92
	v_and_b32_e32 v11, 0xffff0000, v187
	v_mul_f32_e32 v11, v12, v11
	v_mfma_f32_32x32x16_bf16 v[32:47], v[96:99], v[196:199], v[32:47]
	v_cvt_pk_bf16_f32 v143, v0, v11
	s_nop 1
	v_permlane32_swap_b32_e32 v140, v142
	v_permlane32_swap_b32_e32 v141, v143
	global_store_dwordx4 v[252:253], v[140:143], off offset:1056
	v_mul_f32_e32 v0, v48, v92
	s_waitcnt vmcnt(5)
; __device__ __forceinline__ unsigned cvt_pk_bf16(float lo, float hi) { unsigned r; asm volatile("v_cvt_pk_bf16_f32 %0, %1, %2" : "=v"(r) : "v"(lo), "v"(hi)); return r; }
; __device__ __forceinline__ float bf_lo(unsigned w) { return __uint_as_float(w << 16); }
; __device__ __forceinline__ float bf_hi(unsigned w) { return __uint_as_float(w & 0xffff0000u); }
; __device__ __forceinline__ void unit(LAS unsigned char* lds, int b, int h, int qb, const bf16_t* Q, const bf16_t* Kn, const bf16_t* Kr, const bf16_t* VT, const bf16_t* proj, bf16_t* ymix, int wv) {
;     ...
;     for (int blk = 0; blk < 4; ++blk)
; #pragma unroll
;         for (int g = 0; g < 4; ++g) { const int dv = 32 * blk + 8 * g + 4 * hi; const u32x2 gt = gts[blk][g];
;             u32x2 w; w.x = cvt_pk_bf16(o[blk][4 * g + 0] * inv * bf_lo(gt.x), o[blk][4 * g + 1] * inv * bf_hi(gt.x)); w.y = cvt_pk_bf16(o[blk][4 * g + 2] * inv * bf_lo(gt.y), o[blk][4 * g + 3] * inv * bf_hi(gt.y));
;             *(u32x2*)(ymix + tok * DM + 512 + h * 128 + dv) = w; }
	v_permlane32_swap_b32_e32 v188, v190
	v_permlane32_swap_b32_e32 v189, v191
	v_lshlrev_b32_e32 v10, 16, v188
	v_mul_f32_e32 v0, v0, v10
	v_mul_f32_e32 v10, v49, v92
	v_and_b32_e32 v11, 0xffff0000, v188
	v_mul_f32_e32 v10, v10, v11
	v_cvt_pk_bf16_f32 v136, v0, v10
	v_mul_f32_e32 v0, v50, v92
	v_lshlrev_b32_e32 v11, 16, v189
	v_mul_f32_e32 v0, v0, v11
	v_mul_f32_e32 v11, v51, v92
	v_and_b32_e32 v12, 0xffff0000, v189
	v_mul_f32_e32 v11, v11, v12
	v_cvt_pk_bf16_f32 v137, v0, v11
	v_mul_f32_e32 v0, v52, v92
	s_waitcnt vmcnt(5)
	v_lshlrev_b32_e32 v10, 16, v190
	v_mul_f32_e32 v0, v0, v10
	v_mul_f32_e32 v10, v53, v92
	v_and_b32_e32 v11, 0xffff0000, v190
	v_mfma_f32_32x32x16_bf16 v[32:47], v[100:103], v[192:195], v[32:47]
	v_mul_f32_e32 v10, v10, v11
	v_cvt_pk_bf16_f32 v138, v0, v10
	v_mul_f32_e32 v0, v54, v92
	v_lshlrev_b32_e32 v11, 16, v191
	v_mul_f32_e32 v0, v0, v11
	v_mul_f32_e32 v11, v55, v92
	v_and_b32_e32 v12, 0xffff0000, v191
	v_mul_f32_e32 v11, v11, v12
	v_cvt_pk_bf16_f32 v139, v0, v11
	s_nop 1
	v_permlane32_swap_b32_e32 v136, v138
	v_permlane32_swap_b32_e32 v137, v139
	global_store_dwordx4 v[252:253], v[136:139], off offset:1088
	v_mul_f32_e32 v0, v56, v92
	s_waitcnt vmcnt(6)
	v_permlane32_swap_b32_e32 v244, v246
	v_permlane32_swap_b32_e32 v245, v247
	v_lshlrev_b32_e32 v10, 16, v244
	v_mul_f32_e32 v0, v0, v10
	v_mul_f32_e32 v10, v57, v92
	v_and_b32_e32 v11, 0xffff0000, v244
	v_mul_f32_e32 v10, v10, v11
	v_cvt_pk_bf16_f32 v140, v0, v10
	v_mul_f32_e32 v0, v58, v92
	v_lshlrev_b32_e32 v11, 16, v245
	v_mfma_f32_32x32x16_bf16 v[32:47], v[104:107], v[180:183], v[32:47]
	v_mul_f32_e32 v0, v0, v11
	v_mul_f32_e32 v11, v59, v92
	v_and_b32_e32 v12, 0xffff0000, v245
	v_mul_f32_e32 v11, v11, v12
	v_cvt_pk_bf16_f32 v141, v0, v11
	v_mul_f32_e32 v0, v60, v92
	s_waitcnt vmcnt(6)
	v_lshlrev_b32_e32 v10, 16, v246
	v_mul_f32_e32 v0, v0, v10
	v_mul_f32_e32 v10, v61, v92
	v_and_b32_e32 v11, 0xffff0000, v246
	v_mul_f32_e32 v10, v10, v11
	v_cvt_pk_bf16_f32 v142, v0, v10
	v_mul_f32_e32 v0, v62, v92
	v_lshlrev_b32_e32 v11, 16, v247
	v_mul_f32_e32 v0, v0, v11
	v_mul_f32_e32 v11, v63, v92
	v_and_b32_e32 v12, 0xffff0000, v247
	v_mul_f32_e32 v11, v11, v12
	v_cvt_pk_bf16_f32 v143, v0, v11
	s_nop 1
	v_permlane32_swap_b32_e32 v140, v142
	v_permlane32_swap_b32_e32 v141, v143
	global_store_dwordx4 v[252:253], v[140:143], off offset:1120
	v_mul_f32_e32 v0, v32, v92
	s_waitcnt vmcnt(7)
	v_permlane32_swap_b32_e32 v248, v250
	v_permlane32_swap_b32_e32 v249, v251
	v_lshlrev_b32_e32 v10, 16, v248
	v_mul_f32_e32 v0, v0, v10
	v_mul_f32_e32 v10, v33, v92
	v_and_b32_e32 v11, 0xffff0000, v248
	v_mul_f32_e32 v10, v10, v11
	v_cvt_pk_bf16_f32 v136, v0, v10
	v_mul_f32_e32 v0, v34, v92
	v_lshlrev_b32_e32 v11, 16, v249
	v_mul_f32_e32 v0, v0, v11
	v_mul_f32_e32 v11, v35, v92
	v_and_b32_e32 v12, 0xffff0000, v249
	v_mul_f32_e32 v11, v11, v12
	v_cvt_pk_bf16_f32 v137, v0, v11
	v_mul_f32_e32 v0, v36, v92
	s_waitcnt vmcnt(7)
	v_lshlrev_b32_e32 v10, 16, v250
	v_mul_f32_e32 v0, v0, v10
	v_mul_f32_e32 v10, v37, v92
	v_and_b32_e32 v11, 0xffff0000, v250
	v_mfma_f32_32x32x16_bf16 v[16:31], v[112:115], v[192:195], v[16:31]
	v_mul_f32_e32 v10, v10, v11
	v_cvt_pk_bf16_f32 v138, v0, v10
	v_mul_f32_e32 v0, v38, v92
	v_lshlrev_b32_e32 v11, 16, v251
	v_mul_f32_e32 v0, v0, v11
	v_mul_f32_e32 v11, v39, v92
	v_and_b32_e32 v12, 0xffff0000, v251
	v_mul_f32_e32 v11, v11, v12
	v_cvt_pk_bf16_f32 v139, v0, v11
	s_nop 1
	v_permlane32_swap_b32_e32 v136, v138
	v_permlane32_swap_b32_e32 v137, v139
	global_store_dwordx4 v[252:253], v[136:139], off offset:1152
	v_mul_f32_e32 v0, v40, v92
	s_waitcnt vmcnt(7)
	v_permlane32_swap_b32_e32 v156, v158
	v_permlane32_swap_b32_e32 v157, v159
	v_lshlrev_b32_e32 v10, 16, v156
	v_mul_f32_e32 v0, v0, v10
	v_mul_f32_e32 v10, v41, v92
	v_and_b32_e32 v11, 0xffff0000, v156
	v_mul_f32_e32 v10, v10, v11
	v_cvt_pk_bf16_f32 v140, v0, v10
	v_mul_f32_e32 v0, v42, v92
	v_lshlrev_b32_e32 v11, 16, v157
	v_mfma_f32_32x32x16_bf16 v[16:31], v[116:119], v[180:183], v[16:31]
	v_mul_f32_e32 v0, v0, v11
	v_mul_f32_e32 v11, v43, v92
	v_and_b32_e32 v12, 0xffff0000, v157
	v_mul_f32_e32 v11, v11, v12
	v_cvt_pk_bf16_f32 v141, v0, v11
	v_mul_f32_e32 v0, v44, v92
	s_waitcnt vmcnt(7)
	v_lshlrev_b32_e32 v10, 16, v158
	v_mul_f32_e32 v0, v0, v10
	v_mul_f32_e32 v10, v45, v92
	v_and_b32_e32 v11, 0xffff0000, v158
	v_mul_f32_e32 v10, v10, v11
	v_cvt_pk_bf16_f32 v142, v0, v10
	v_mul_f32_e32 v0, v46, v92
	v_lshlrev_b32_e32 v11, 16, v159
	v_mul_f32_e32 v0, v0, v11
	v_mul_f32_e32 v11, v47, v92
	v_and_b32_e32 v12, 0xffff0000, v159
	v_mul_f32_e32 v11, v11, v12
	v_cvt_pk_bf16_f32 v143, v0, v11
	s_nop 1
	v_permlane32_swap_b32_e32 v140, v142
	v_permlane32_swap_b32_e32 v141, v143
	global_store_dwordx4 v[252:253], v[140:143], off offset:1184
	v_mul_f32_e32 v0, v16, v92
	s_waitcnt vmcnt(7)
	v_permlane32_swap_b32_e32 v160, v162
	v_permlane32_swap_b32_e32 v161, v163
	v_lshlrev_b32_e32 v10, 16, v160
	v_mul_f32_e32 v0, v0, v10
	v_mul_f32_e32 v10, v17, v92
	v_and_b32_e32 v11, 0xffff0000, v160
	v_mul_f32_e32 v10, v10, v11
	v_cvt_pk_bf16_f32 v136, v0, v10
	v_mul_f32_e32 v0, v18, v92
	v_lshlrev_b32_e32 v11, 16, v161
	v_mul_f32_e32 v0, v0, v11
	v_mul_f32_e32 v11, v19, v92
	v_and_b32_e32 v12, 0xffff0000, v161
	v_mul_f32_e32 v11, v11, v12
	v_cvt_pk_bf16_f32 v137, v0, v11
	v_mul_f32_e32 v0, v20, v92
	s_waitcnt vmcnt(7)
	v_lshlrev_b32_e32 v10, 16, v162
	v_mul_f32_e32 v0, v0, v10
	v_mul_f32_e32 v10, v21, v92
	v_and_b32_e32 v8, 0xffff0000, v162
	v_mul_f32_e32 v8, v10, v8
	v_cvt_pk_bf16_f32 v138, v0, v8
	v_mul_f32_e32 v0, v22, v92
	v_lshlrev_b32_e32 v10, 16, v163
	v_mul_f32_e32 v0, v0, v10
	v_mul_f32_e32 v10, v23, v92
	v_and_b32_e32 v9, 0xffff0000, v163
	v_mul_f32_e32 v9, v10, v9
	v_cvt_pk_bf16_f32 v139, v0, v9
	s_nop 1
	v_permlane32_swap_b32_e32 v136, v138
	v_permlane32_swap_b32_e32 v137, v139
	global_store_dwordx4 v[252:253], v[136:139], off offset:1216
	v_mul_f32_e32 v0, v24, v92
	s_waitcnt vmcnt(7)
	v_permlane32_swap_b32_e32 v164, v166
	v_permlane32_swap_b32_e32 v165, v167
	v_lshlrev_b32_e32 v8, 16, v164
	v_mul_f32_e32 v0, v0, v8
	v_mul_f32_e32 v8, v25, v92
	v_and_b32_e32 v4, 0xffff0000, v164
	v_mul_f32_e32 v4, v8, v4
	v_cvt_pk_bf16_f32 v140, v0, v4
	v_mul_f32_e32 v0, v26, v92
	v_lshlrev_b32_e32 v8, 16, v165
	v_mul_f32_e32 v0, v0, v8
	v_mul_f32_e32 v8, v27, v92
	v_and_b32_e32 v5, 0xffff0000, v165
	v_mul_f32_e32 v5, v8, v5
	v_cvt_pk_bf16_f32 v141, v0, v5
	v_mul_f32_e32 v0, v28, v92
	s_waitcnt vmcnt(7)
	v_lshlrev_b32_e32 v4, 16, v166
	v_mul_f32_e32 v0, v0, v4
	v_mul_f32_e32 v4, v29, v92
	v_and_b32_e32 v2, 0xffff0000, v166
	v_mul_f32_e32 v2, v4, v2
	v_cvt_pk_bf16_f32 v142, v0, v2
	v_mul_f32_e32 v0, v30, v92
	v_lshlrev_b32_e32 v4, 16, v167
	v_mul_f32_e32 v0, v0, v4
	v_mul_f32_e32 v4, v31, v92
	v_and_b32_e32 v3, 0xffff0000, v167
	v_mul_f32_e32 v3, v4, v3
	v_cvt_pk_bf16_f32 v143, v0, v3
	s_nop 1
	v_permlane32_swap_b32_e32 v140, v142
	v_permlane32_swap_b32_e32 v141, v143
	global_store_dwordx4 v[252:253], v[140:143], off offset:1248
	s_cbranch_scc0 .LBB0_633

.LBB0_624:
	v_add_u32_e32 v0, s70, v215
	ds_read_b128 v[2:5], v0
	ds_read_b128 v[6:9], v0 offset:32
	v_mov_b64_e32 v[110:111], v[94:95]
	v_mov_b64_e32 v[108:109], v[92:93]
	v_mov_b64_e32 v[106:107], v[90:91]
	s_waitcnt lgkmcnt(1)
	v_mfma_f32_32x32x16_bf16 v[112:127], v[2:5], v[128:131], v[80:95]
	ds_read_b128 v[2:5], v0 offset:12800
	ds_read_b128 v[10:13], v0 offset:12832
	v_mov_b64_e32 v[104:105], v[88:89]
	v_mov_b64_e32 v[102:103], v[86:87]
	v_mov_b64_e32 v[100:101], v[84:85]
	v_mov_b64_e32 v[98:99], v[82:83]
	v_mov_b64_e32 v[96:97], v[80:81]
	s_waitcnt lgkmcnt(2)
	v_mfma_f32_32x32x16_bf16 v[112:127], v[6:9], v[132:135], v[112:127]
	s_add_i32 s12, s58, 0xffffffa0
	s_lshl_b64 s[8:9], s[12:13], 1
	s_waitcnt lgkmcnt(1)
	v_mfma_f32_32x32x16_bf16 v[96:111], v[2:5], v[128:131], v[96:111]
	ds_read_b128 v[2:5], v0 offset:64
	ds_read_b128 v[6:9], v0 offset:96
	s_waitcnt lgkmcnt(2)
	v_mfma_f32_32x32x16_bf16 v[96:111], v[10:13], v[132:135], v[96:111]
	s_waitcnt lgkmcnt(1)
	v_mfma_f32_32x32x16_bf16 v[112:127], v[2:5], v[136:139], v[112:127]
	ds_read_b128 v[2:5], v0 offset:12864
	ds_read_b128 v[10:13], v0 offset:12896
	s_waitcnt lgkmcnt(1)
	v_mfma_f32_32x32x16_bf16 v[96:111], v[2:5], v[136:139], v[96:111]
	v_mfma_f32_32x32x16_bf16 v[112:127], v[6:9], v[140:143], v[112:127]
	ds_read_b128 v[2:5], v0 offset:128
	ds_read_b128 v[6:9], v0 offset:160
	s_waitcnt lgkmcnt(2)
	v_mfma_f32_32x32x16_bf16 v[96:111], v[10:13], v[140:143], v[96:111]
	s_waitcnt lgkmcnt(1)
	v_mfma_f32_32x32x16_bf16 v[112:127], v[2:5], v[144:147], v[112:127]
	ds_read_b128 v[2:5], v0 offset:12928
	ds_read_b128 v[10:13], v0 offset:12960
	s_waitcnt lgkmcnt(1)
	v_mfma_f32_32x32x16_bf16 v[96:111], v[2:5], v[144:147], v[96:111]
	v_mfma_f32_32x32x16_bf16 v[112:127], v[6:9], v[148:151], v[112:127]
	ds_read_b128 v[2:5], v0 offset:192
	ds_read_b128 v[6:9], v0 offset:224
	s_waitcnt lgkmcnt(2)
	v_mfma_f32_32x32x16_bf16 v[96:111], v[10:13], v[148:151], v[96:111]
	s_waitcnt lgkmcnt(1)
	v_mfma_f32_32x32x16_bf16 v[112:127], v[2:5], v[152:155], v[112:127]
	ds_read_b128 v[2:5], v0 offset:12992
	ds_read_b128 v[10:13], v0 offset:13024
	s_waitcnt lgkmcnt(1)
	v_mfma_f32_32x32x16_bf16 v[96:111], v[2:5], v[152:155], v[96:111]
	v_mfma_f32_32x32x16_bf16 v[112:127], v[6:9], v[156:159], v[112:127]
	ds_read_b128 v[2:5], v0 offset:256
	ds_read_b128 v[6:9], v0 offset:288
	s_waitcnt lgkmcnt(2)
	v_mfma_f32_32x32x16_bf16 v[96:111], v[10:13], v[156:159], v[96:111]
	s_waitcnt lgkmcnt(1)
	v_mfma_f32_32x32x16_bf16 v[112:127], v[2:5], v[160:163], v[112:127]
	ds_read_b128 v[2:5], v0 offset:13056
	ds_read_b128 v[10:13], v0 offset:13088
	s_waitcnt lgkmcnt(1)
	v_mfma_f32_32x32x16_bf16 v[96:111], v[2:5], v[160:163], v[96:111]
	v_mfma_f32_32x32x16_bf16 v[112:127], v[6:9], v[164:167], v[112:127]
	ds_read_b128 v[2:5], v0 offset:320
	ds_read_b128 v[6:9], v0 offset:352
	s_waitcnt lgkmcnt(2)
	v_mfma_f32_32x32x16_bf16 v[96:111], v[10:13], v[164:167], v[96:111]
	s_waitcnt lgkmcnt(1)
	v_mfma_f32_32x32x16_bf16 v[112:127], v[2:5], v[168:171], v[112:127]
	ds_read_b128 v[2:5], v0 offset:13120
	ds_read_b128 v[10:13], v0 offset:13152
	s_waitcnt lgkmcnt(1)
	v_mfma_f32_32x32x16_bf16 v[96:111], v[2:5], v[168:171], v[96:111]
	v_lshl_add_u64 v[2:3], v[206:207], 0, s[8:9]
	v_lshl_add_u64 v[4:5], v[218:219], 0, s[8:9]
	v_mfma_f32_32x32x16_bf16 v[112:127], v[6:9], v[172:175], v[112:127]
	s_and_b64 vcc, exec, s[60:61]
	s_cbranch_vccz .Llg_a
	global_load_dwordx4 v[156:159], v[252:253], off offset:160
	global_load_dwordx4 v[160:163], v[252:253], off offset:192
	global_load_dwordx4 v[164:167], v[252:253], off offset:224
.Llg_a:
	global_load_dwordx4 v[6:9], v[2:3], off
	s_nop 0
	global_load_dwordx4 v[2:5], v[4:5], off
	s_waitcnt lgkmcnt(0)
	v_mfma_f32_32x32x16_bf16 v[96:111], v[10:13], v[172:175], v[96:111]
	s_add_i32 s8, s75, 0
	s_add_i32 s8, s8, 0x12c00
	v_add_u32_e32 v0, s8, v227
	v_add_u32_e32 v221, v0, v226
	ds_read2_b64 v[10:13], v221 offset1:2
	v_add_u32_e32 v0, s58, v225
	v_add_u32_e32 v220, 0x1000, v221
	ds_read2_b64 v[236:239], v220 offset0:32 offset1:34
	s_waitcnt lgkmcnt(1)
	v_mfma_f32_32x32x16_bf16 v[64:79], v[10:13], v[200:203], v[64:79]
	v_add_u32_e32 v10, 0xffffffa0, v0
	v_cmp_le_i32_e32 vcc, v10, v216
	v_subrev_u32_e32 v12, 64, v0
	s_nop 0
	v_cndmask_b32_e32 v11, v224, v112, vcc
	v_cmp_le_i32_e32 vcc, v12, v216
	v_max_f32_e32 v12, v11, v11
	v_max_f32_e32 v12, 0xff800000, v12
	v_cndmask_b32_e32 v231, v224, v96, vcc
	v_cmp_lt_i32_e32 vcc, v10, v216
	v_subrev_u32_e32 v10, 63, v0
	s_nop 0
	v_cndmask_b32_e32 v233, v11, v112, vcc
	v_cndmask_b32_e32 v232, v224, v113, vcc
	v_cmp_le_i32_e32 vcc, v10, v216
	v_add_u32_e32 v11, 0xffffffa2, v0
	s_nop 0
	v_cndmask_b32_e32 v234, v224, v97, vcc
	v_cmp_le_i32_e32 vcc, v11, v216
	v_subrev_u32_e32 v11, 62, v0
	v_max3_f32 v10, v231, s64, v234
	v_cndmask_b32_e32 v14, v224, v114, vcc
	v_cmp_le_i32_e32 vcc, v11, v216
	v_add_u32_e32 v11, 0xffffffa3, v0
	s_nop 0
	v_cndmask_b32_e32 v96, v224, v98, vcc
	v_cmp_le_i32_e32 vcc, v11, v216
	v_subrev_u32_e32 v11, 61, v0
	v_max3_f32 v98, v12, v232, v14
	v_cndmask_b32_e32 v15, v224, v115, vcc
	v_cmp_le_i32_e32 vcc, v11, v216
	s_nop 1
	v_cndmask_b32_e32 v97, v224, v99, vcc
	v_max3_f32 v99, v10, v96, v97
	v_add_u32_e32 v112, 0xffffffa8, v0
	v_cmp_le_i32_e32 vcc, v112, v216
	v_subrev_u32_e32 v113, 56, v0
	s_waitcnt lgkmcnt(0)
	v_mfma_f32_32x32x16_bf16 v[48:63], v[236:239], v[200:203], v[48:63]
	v_cndmask_b32_e32 v112, v224, v116, vcc
	v_cmp_le_i32_e32 vcc, v113, v216
	v_max3_f32 v114, v98, v15, v112
	v_add_u32_e32 v98, 0xffffffa9, v0
	v_cndmask_b32_e32 v116, v224, v100, vcc
	v_cmp_le_i32_e32 vcc, v98, v216
	v_subrev_u32_e32 v98, 55, v0
	v_add_u32_e32 v229, 0x2000, v221
	v_cndmask_b32_e32 v113, v224, v117, vcc
	v_cmp_le_i32_e32 vcc, v98, v216
	v_add_u32_e32 v98, 0xffffffaa, v0
	ds_read2_b64 v[10:13], v229 offset0:64 offset1:66
	v_cndmask_b32_e32 v117, v224, v101, vcc
	v_max3_f32 v115, v99, v116, v117
	v_cmp_le_i32_e32 vcc, v98, v216
	v_subrev_u32_e32 v99, 54, v0
	v_subrev_u32_e32 v101, 53, v0
	v_cndmask_b32_e32 v98, v224, v118, vcc
	v_cmp_le_i32_e32 vcc, v99, v216
	v_add_u32_e32 v99, 0xffffffab, v0
	s_nop 0
	v_cndmask_b32_e32 v100, v224, v102, vcc
	v_cmp_le_i32_e32 vcc, v99, v216
	v_max3_f32 v102, v114, v113, v98
	s_nop 0
	v_cndmask_b32_e32 v99, v224, v119, vcc
	v_cmp_le_i32_e32 vcc, v101, v216
	s_nop 1
	v_cndmask_b32_e32 v101, v224, v103, vcc
	v_max3_f32 v103, v115, v100, v101
	s_waitcnt lgkmcnt(0)
	v_mfma_f32_32x32x16_bf16 v[32:47], v[10:13], v[200:203], v[32:47]
	v_add_u32_e32 v10, 0xffffffb0, v0
	v_cmp_le_i32_e32 vcc, v10, v216
	v_subrev_u32_e32 v10, 48, v0
	v_add_u32_e32 v11, 0xffffffb1, v0
	v_cndmask_b32_e32 v114, v224, v120, vcc
	v_cmp_le_i32_e32 vcc, v10, v216
	v_add_u32_e32 v12, 0xffffffb2, v0
	v_add_u32_e32 v230, 0x3000, v221
	v_cndmask_b32_e32 v118, v224, v104, vcc
	v_cmp_le_i32_e32 vcc, v11, v216
	v_subrev_u32_e32 v11, 47, v0
	v_max3_f32 v10, v102, v99, v114
	v_cndmask_b32_e32 v115, v224, v121, vcc
	v_cmp_le_i32_e32 vcc, v11, v216
	ds_read2_b64 v[236:239], v230 offset0:96 offset1:98
	s_nop 0
	v_cndmask_b32_e32 v119, v224, v105, vcc
	v_cmp_le_i32_e32 vcc, v12, v216
	v_subrev_u32_e32 v12, 46, v0
	v_max3_f32 v11, v103, v118, v119
	v_cndmask_b32_e32 v102, v224, v122, vcc
	v_cmp_le_i32_e32 vcc, v12, v216
	v_add_u32_e32 v12, 0xffffffb3, v0
	v_max3_f32 v10, v10, v115, v102
	v_cndmask_b32_e32 v104, v224, v106, vcc
	v_cmp_le_i32_e32 vcc, v12, v216
	v_subrev_u32_e32 v12, 45, v0
	s_nop 0
	v_cndmask_b32_e32 v103, v224, v123, vcc
	v_cmp_le_i32_e32 vcc, v12, v216
	s_nop 1
	v_cndmask_b32_e32 v105, v224, v107, vcc
	v_max3_f32 v11, v11, v104, v105
	v_add_u32_e32 v12, 0xffffffb8, v0
	v_cmp_le_i32_e32 vcc, v12, v216
	v_subrev_u32_e32 v12, 40, v0
	s_waitcnt lgkmcnt(0)
	v_mfma_f32_32x32x16_bf16 v[16:31], v[236:239], v[200:203], v[16:31]
	v_cndmask_b32_e32 v106, v224, v124, vcc
	v_cmp_le_i32_e32 vcc, v12, v216
	v_add_u32_e32 v12, 0xffffffb9, v0
	v_max3_f32 v10, v10, v103, v106
	v_cndmask_b32_e32 v120, v224, v108, vcc
	v_cmp_le_i32_e32 vcc, v12, v216
	v_subrev_u32_e32 v12, 39, v0
	ds_read2_b64 v[240:243], v221 offset0:4 offset1:6
	v_cndmask_b32_e32 v107, v224, v125, vcc
	v_cmp_le_i32_e32 vcc, v12, v216
	v_add_u32_e32 v12, 0xffffffba, v0
	s_nop 0
	v_cndmask_b32_e32 v121, v224, v109, vcc
	v_cmp_le_i32_e32 vcc, v12, v216
	v_subrev_u32_e32 v12, 38, v0
	v_max3_f32 v11, v11, v120, v121
	v_cndmask_b32_e32 v124, v224, v126, vcc
	v_cmp_le_i32_e32 vcc, v12, v216
	s_nop 1
	v_cndmask_b32_e32 v125, v224, v110, vcc
	v_max3_f32 v110, v10, v107, v124
	v_add_u32_e32 v10, 0xffffffbb, v0
	v_cmp_le_i32_e32 vcc, v10, v216
	v_subrev_u32_e32 v0, 37, v0
	s_nop 0
	v_cndmask_b32_e32 v108, v224, v127, vcc
	v_cmp_le_i32_e32 vcc, v0, v216
	s_nop 1
	v_cndmask_b32_e32 v109, v224, v111, vcc
	v_max3_f32 v0, v11, v125, v109
	v_max3_f32 v0, v110, v108, v0
	v_mov_b32_e32 v110, v0
	ds_read2_b64 v[10:13], v220 offset0:36 offset1:38
	s_waitcnt lgkmcnt(1)
	v_mfma_f32_32x32x16_bf16 v[64:79], v[240:243], v[196:199], v[64:79]
	v_permlane32_swap_b32_e32 v110, v0
	v_max_f32_e32 v110, v110, v110
	v_max_f32_e32 v0, v0, v110
	v_cmp_lt_f32_e32 vcc, s65, v0
	s_cbranch_vccz .LBB0_626
	v_max_f32_e32 v0, v0, v0
	v_max_f32_e32 v0, 0, v0
	v_add_f32_e32 v217, v217, v0
	v_sub_f32_e32 v233, v233, v0
	v_sub_f32_e32 v232, v232, v0
	v_sub_f32_e32 v231, v231, v0
	v_sub_f32_e32 v234, v234, v0
	v_pk_add_f32 v[14:15], v[14:15], v[0:1] op_sel_hi:[1,0] neg_lo:[0,1] neg_hi:[0,1]
	v_pk_add_f32 v[96:97], v[96:97], v[0:1] op_sel_hi:[1,0] neg_lo:[0,1] neg_hi:[0,1]
	v_pk_add_f32 v[112:113], v[112:113], v[0:1] op_sel_hi:[1,0] neg_lo:[0,1] neg_hi:[0,1]
	v_pk_add_f32 v[116:117], v[116:117], v[0:1] op_sel_hi:[1,0] neg_lo:[0,1] neg_hi:[0,1]
	v_pk_add_f32 v[98:99], v[98:99], v[0:1] op_sel_hi:[1,0] neg_lo:[0,1] neg_hi:[0,1]
	v_pk_add_f32 v[100:101], v[100:101], v[0:1] op_sel_hi:[1,0] neg_lo:[0,1] neg_hi:[0,1]
	v_pk_add_f32 v[114:115], v[114:115], v[0:1] op_sel_hi:[1,0] neg_lo:[0,1] neg_hi:[0,1]
	v_pk_add_f32 v[118:119], v[118:119], v[0:1] op_sel_hi:[1,0] neg_lo:[0,1] neg_hi:[0,1]
	v_pk_add_f32 v[102:103], v[102:103], v[0:1] op_sel_hi:[1,0] neg_lo:[0,1] neg_hi:[0,1]
	v_pk_add_f32 v[104:105], v[104:105], v[0:1] op_sel_hi:[1,0] neg_lo:[0,1] neg_hi:[0,1]
	v_pk_add_f32 v[106:107], v[106:107], v[0:1] op_sel_hi:[1,0] neg_lo:[0,1] neg_hi:[0,1]
	v_pk_add_f32 v[120:121], v[120:121], v[0:1] op_sel_hi:[1,0] neg_lo:[0,1] neg_hi:[0,1]
	v_sub_f32_e32 v124, v124, v0
	v_sub_f32_e32 v125, v125, v0
	v_pk_add_f32 v[108:109], v[108:109], v[0:1] op_sel_hi:[1,0] neg_lo:[0,1] neg_hi:[0,1]
	v_exp_f32_e64 v0, -v0
	v_xor_b32_e32 v80, 0x80000000, v217
	v_mov_b32_e32 v81, v80
	v_mov_b32_e32 v82, v80
	v_mov_b32_e32 v83, v80
	v_mov_b32_e32 v84, v80
	v_mov_b32_e32 v85, v80
	v_mov_b32_e32 v86, v80
	v_mov_b32_e32 v87, v80
	v_mov_b32_e32 v88, v80
	v_mov_b32_e32 v89, v80
	v_mov_b32_e32 v90, v80
	v_mov_b32_e32 v91, v80
	v_mov_b32_e32 v92, v80
	v_mov_b32_e32 v93, v80
	v_mov_b32_e32 v94, v80
	v_mov_b32_e32 v95, v80
	s_branch .LBB0_627

; __device__ __forceinline__ unsigned cvt_pk_bf16(float lo, float hi) { unsigned r; asm volatile("v_cvt_pk_bf16_f32 %0, %1, %2" : "=v"(r) : "v"(lo), "v"(hi)); return r; }
; __device__ __forceinline__ float bf_lo(unsigned w) { return __uint_as_float(w << 16); }
; __device__ __forceinline__ float bf_hi(unsigned w) { return __uint_as_float(w & 0xffff0000u); }
; __device__ __forceinline__ void unit(LAS unsigned char* lds, int b, int h, int qb, const bf16_t* Q, const bf16_t* Kn, const bf16_t* Kr, const bf16_t* VT, const bf16_t* proj, bf16_t* ymix, int wv) {
;     ...
;     lrun += shfl_xor_f(lrun, 32);
;     const float inv = 1.f / lrun;
;     const size_t tok = (size_t)tok0 + qidx;
;     u32x2 gts[4][4];
; #pragma unroll
;     for (int blk = 0; blk < 4; ++blk)
; #pragma unroll
;         for (int g = 0; g < 4; ++g) gts[blk][g] = *(const u32x2*)(proj + tok * NIN + PJ_BG + h * 128 + 32 * blk + 8 * g + 4 * hi);
; #pragma unroll
;     for (int blk = 0; blk < 4; ++blk)
; #pragma unroll
;         for (int g = 0; g < 4; ++g) { const int dv = 32 * blk + 8 * g + 4 * hi; const u32x2 gt = gts[blk][g];
;             u32x2 w; w.x = cvt_pk_bf16(o[blk][4 * g + 0] * inv * bf_lo(gt.x), o[blk][4 * g + 1] * inv * bf_hi(gt.x)); w.y = cvt_pk_bf16(o[blk][4 * g + 2] * inv * bf_lo(gt.y), o[blk][4 * g + 3] * inv * bf_hi(gt.y));
;             *(u32x2*)(ymix + tok * DM + 512 + h * 128 + dv) = w; }
.LBB0_1170:
	s_add_i32 s6, s58, 0
	s_add_i32 s6, s6, 0x12c00
	v_add3_u32 v0, s6, v227, v226
	ds_read2_b64 v[2:5], v0 offset1:2
	v_ashrrev_i32_e32 v217, 31, v216
	v_mov_b64_e32 v[6:7], s[46:47]
	v_lshl_add_u64 v[120:121], v[216:217], 0, s[16:17]
	v_mad_u64_u32 v[122:123], s[16:17], v120, s54, v[6:7]
	ds_read2_b64 v[6:9], v0 offset0:4 offset1:6
	ds_read2_b64 v[12:15], v0 offset0:8 offset1:10
	v_add_u32_e32 v88, 0x1000, v0
	v_add_u32_e32 v104, 0x2000, v0
	s_waitcnt lgkmcnt(2)
	v_mfma_f32_32x32x16_bf16 v[64:79], v[2:5], v[200:203], v[64:79]
	ds_read2_b64 v[2:5], v0 offset0:12 offset1:14
	v_add_u32_e32 v0, 0x3000, v0
	v_mad_i32_i24 v123, v121, s54, v123
	s_lshl_b32 s6, s56, 1
	ds_read2_b64 v[80:83], v88 offset0:32 offset1:34
	ds_read2_b64 v[84:87], v88 offset0:36 offset1:38
	v_mov_b32_e32 v11, v222
	s_add_i32 s3, s3, s31
	s_waitcnt lgkmcnt(4)
	v_mfma_f32_32x32x16_bf16 v[64:79], v[6:9], v[196:199], v[64:79]
	ds_read2_b64 v[6:9], v88 offset0:40 offset1:42
	ds_read2_b64 v[88:91], v88 offset0:44 offset1:46
	ds_read2_b64 v[92:95], v104 offset0:64 offset1:66
	ds_read2_b64 v[96:99], v104 offset0:68 offset1:70
	ds_read2_b64 v[100:103], v104 offset0:72 offset1:74
	ds_read2_b64 v[104:107], v104 offset0:76 offset1:78
	ds_read2_b64 v[108:111], v0 offset0:96 offset1:98
	s_cmpk_lt_i32 s3, 0x400
	s_waitcnt lgkmcnt(10)
	v_mfma_f32_32x32x16_bf16 v[64:79], v[12:15], v[192:195], v[64:79]
	ds_read2_b64 v[12:15], v0 offset0:100 offset1:102
	ds_read2_b64 v[112:115], v0 offset0:104 offset1:106
	ds_read2_b64 v[116:119], v0 offset0:108 offset1:110
	v_lshlrev_b32_e32 v0, 1, v225
	s_waitcnt lgkmcnt(0)
	s_barrier
	v_mfma_f32_32x32x16_bf16 v[64:79], v[2:5], v[188:191], v[64:79]
	v_lshl_add_u64 v[2:3], v[122:123], 0, s[6:7]
	v_lshl_add_u64 v[2:3], v[2:3], 0, v[0:1]
	v_add_co_u32_e32 v4, vcc, s55, v2
	s_nop 1
	v_addc_co_u32_e32 v5, vcc, 0, v3, vcc
	v_and_b32_e32 v168, 32, v222
	v_lshrrev_b32_e32 v168, 2, v168
	v_mov_b32_e32 v169, 0
	v_lshl_add_u64 v[168:169], v[4:5], 0, v[168:169]
	v_lshl_add_u64 v[2:3], v[2:3], 0, s[10:11]
	v_mfma_f32_32x32x16_bf16 v[48:63], v[80:83], v[200:203], v[48:63]
	v_lshlrev_b32_e32 v4, 2, v11
	v_xor_b32_e32 v4, 0x80, v4
	ds_bpermute_b32 v4, v4, v10
	v_mfma_f32_32x32x16_bf16 v[48:63], v[84:87], v[196:199], v[48:63]
	v_mfma_f32_32x32x16_bf16 v[48:63], v[6:9], v[192:195], v[48:63]
	s_waitcnt lgkmcnt(0)
	v_add_f32_e32 v6, v10, v4
	v_div_scale_f32 v7, s[16:17], v6, v6, 1.0
	v_rcp_f32_e32 v134, v7
	v_mfma_f32_32x32x16_bf16 v[48:63], v[88:91], v[188:191], v[48:63]
	s_nop 0
	v_mfma_f32_32x32x16_bf16 v[32:47], v[92:95], v[200:203], v[32:47]
	v_fma_f32 v92, -v7, v134, 1.0
	v_fmac_f32_e32 v134, v92, v134
	v_div_scale_f32 v92, vcc, 1.0, v6, 1.0
	v_mul_f32_e32 v93, v92, v134
	v_fma_f32 v94, -v7, v93, v92
	v_fmac_f32_e32 v93, v94, v134
	v_fma_f32 v7, -v7, v93, v92
	v_mfma_f32_32x32x16_bf16 v[16:31], v[108:111], v[200:203], v[16:31]
	v_div_fmas_f32 v7, v7, v134, v93
	v_div_fixup_f32 v92, v7, v6, 1.0
	v_mul_f32_e32 v64, v64, v92
	v_lshlrev_b64 v[6:7], 12, v[120:121]
	v_mul_f32_e32 v65, v65, v92
	v_lshl_add_u64 v[6:7], s[22:23], 0, v[6:7]
	v_lshl_add_u64 v[6:7], v[6:7], 0, s[6:7]
	v_lshl_add_u64 v[6:7], v[6:7], 0, v[0:1]
	v_mul_f32_e32 v0, v68, v92
	v_mfma_f32_32x32x16_bf16 v[16:31], v[12:15], v[196:199], v[16:31]
	v_mul_f32_e32 v12, v69, v92
	s_waitcnt vmcnt(3)
	v_permlane32_swap_b32_e32 v176, v178
	v_permlane32_swap_b32_e32 v177, v179
	v_lshlrev_b32_e32 v93, 16, v176
	v_mul_f32_e32 v64, v64, v93
	v_and_b32_e32 v93, 0xffff0000, v176
	v_mul_f32_e32 v65, v65, v93
	v_cvt_pk_bf16_f32 v136, v64, v65
	v_mul_f32_e32 v65, v66, v92
	v_lshlrev_b32_e32 v66, 16, v177
	v_mul_f32_e32 v65, v65, v66
	v_mul_f32_e32 v66, v67, v92
	v_and_b32_e32 v67, 0xffff0000, v177
	v_mul_f32_e32 v66, v66, v67
	v_cvt_pk_bf16_f32 v137, v65, v66
	v_and_b32_e32 v252, 32, v222
	v_lshrrev_b32_e32 v252, 2, v252
	v_mov_b32_e32 v253, 0
	v_lshl_add_u64 v[252:253], v[6:7], 0, v[252:253]
	s_waitcnt vmcnt(3)
	v_lshlrev_b32_e32 v64, 16, v178
	v_and_b32_e32 v13, 0xffff0000, v178
	v_mul_f32_e32 v0, v0, v64
	v_mul_f32_e32 v12, v12, v13
	v_cvt_pk_bf16_f32 v138, v0, v12
	v_mul_f32_e32 v0, v70, v92
	v_lshlrev_b32_e32 v13, 16, v179
	v_mul_f32_e32 v0, v0, v13
	v_mul_f32_e32 v13, v71, v92
	v_and_b32_e32 v14, 0xffff0000, v179
	v_mul_f32_e32 v13, v13, v14
	v_cvt_pk_bf16_f32 v139, v0, v13
	s_nop 1
	v_permlane32_swap_b32_e32 v136, v138
	v_permlane32_swap_b32_e32 v137, v139
	global_store_dwordx4 v[252:253], v[136:139], off offset:1024
	v_mul_f32_e32 v0, v72, v92
	s_waitcnt vmcnt(4)
	v_permlane32_swap_b32_e32 v180, v182
	v_permlane32_swap_b32_e32 v181, v183
	v_lshlrev_b32_e32 v12, 16, v180
	v_mul_f32_e32 v0, v0, v12
	v_mul_f32_e32 v12, v73, v92
	v_and_b32_e32 v13, 0xffff0000, v180
	v_mul_f32_e32 v12, v12, v13
	v_cvt_pk_bf16_f32 v140, v0, v12
	v_mul_f32_e32 v0, v74, v92
	v_lshlrev_b32_e32 v13, 16, v181
	v_mul_f32_e32 v0, v0, v13
	v_mul_f32_e32 v13, v75, v92
	v_and_b32_e32 v14, 0xffff0000, v181
	v_mul_f32_e32 v13, v13, v14
	v_cvt_pk_bf16_f32 v141, v0, v13
	v_mul_f32_e32 v0, v76, v92
	s_waitcnt vmcnt(4)
	v_lshlrev_b32_e32 v12, 16, v182
	v_mul_f32_e32 v0, v0, v12
	v_mul_f32_e32 v12, v77, v92
	v_and_b32_e32 v10, 0xffff0000, v182
	v_mul_f32_e32 v10, v12, v10
	v_cvt_pk_bf16_f32 v142, v0, v10
	v_mul_f32_e32 v0, v78, v92
	v_lshlrev_b32_e32 v12, 16, v183
	v_mul_f32_e32 v0, v0, v12
	v_mul_f32_e32 v12, v79, v92
	v_and_b32_e32 v11, 0xffff0000, v183
	v_mul_f32_e32 v11, v12, v11
	v_mfma_f32_32x32x16_bf16 v[32:47], v[96:99], v[196:199], v[32:47]
	v_cvt_pk_bf16_f32 v143, v0, v11
	s_nop 1
	v_permlane32_swap_b32_e32 v140, v142
	v_permlane32_swap_b32_e32 v141, v143
	global_store_dwordx4 v[252:253], v[140:143], off offset:1056
	v_mul_f32_e32 v0, v48, v92
	s_waitcnt vmcnt(5)
; __device__ __forceinline__ unsigned cvt_pk_bf16(float lo, float hi) { unsigned r; asm volatile("v_cvt_pk_bf16_f32 %0, %1, %2" : "=v"(r) : "v"(lo), "v"(hi)); return r; }
; __device__ __forceinline__ float bf_lo(unsigned w) { return __uint_as_float(w << 16); }
; __device__ __forceinline__ float bf_hi(unsigned w) { return __uint_as_float(w & 0xffff0000u); }
; __device__ __forceinline__ void unit(LAS unsigned char* lds, int b, int h, int qb, const bf16_t* Q, const bf16_t* Kn, const bf16_t* Kr, const bf16_t* VT, const bf16_t* proj, bf16_t* ymix, int wv) {
;     ...
;     for (int blk = 0; blk < 4; ++blk)
; #pragma unroll
;         for (int g = 0; g < 4; ++g) { const int dv = 32 * blk + 8 * g + 4 * hi; const u32x2 gt = gts[blk][g];
;             u32x2 w; w.x = cvt_pk_bf16(o[blk][4 * g + 0] * inv * bf_lo(gt.x), o[blk][4 * g + 1] * inv * bf_hi(gt.x)); w.y = cvt_pk_bf16(o[blk][4 * g + 2] * inv * bf_lo(gt.y), o[blk][4 * g + 3] * inv * bf_hi(gt.y));
;             *(u32x2*)(ymix + tok * DM + 512 + h * 128 + dv) = w; }
	v_permlane32_swap_b32_e32 v184, v186
	v_permlane32_swap_b32_e32 v185, v187
	v_lshlrev_b32_e32 v10, 16, v184
	v_mul_f32_e32 v0, v0, v10
	v_mul_f32_e32 v10, v49, v92
	v_and_b32_e32 v11, 0xffff0000, v184
	v_mul_f32_e32 v10, v10, v11
	v_cvt_pk_bf16_f32 v136, v0, v10
	v_mul_f32_e32 v0, v50, v92
	v_lshlrev_b32_e32 v11, 16, v185
	v_mul_f32_e32 v0, v0, v11
	v_mul_f32_e32 v11, v51, v92
	v_and_b32_e32 v12, 0xffff0000, v185
	v_mul_f32_e32 v11, v11, v12
	v_cvt_pk_bf16_f32 v137, v0, v11
	v_mul_f32_e32 v0, v52, v92
	s_waitcnt vmcnt(5)
	v_lshlrev_b32_e32 v10, 16, v186
	v_mul_f32_e32 v0, v0, v10
	v_mul_f32_e32 v10, v53, v92
	v_and_b32_e32 v11, 0xffff0000, v186
	v_mfma_f32_32x32x16_bf16 v[32:47], v[100:103], v[192:195], v[32:47]
	v_mul_f32_e32 v10, v10, v11
	v_cvt_pk_bf16_f32 v138, v0, v10
	v_mul_f32_e32 v0, v54, v92
	v_lshlrev_b32_e32 v11, 16, v187
	v_mul_f32_e32 v0, v0, v11
	v_mul_f32_e32 v11, v55, v92
	v_and_b32_e32 v12, 0xffff0000, v187
	v_mul_f32_e32 v11, v11, v12
	v_cvt_pk_bf16_f32 v139, v0, v11
	s_nop 1
	v_permlane32_swap_b32_e32 v136, v138
	v_permlane32_swap_b32_e32 v137, v139
	global_store_dwordx4 v[252:253], v[136:139], off offset:1088
	v_mul_f32_e32 v0, v56, v92
	s_waitcnt vmcnt(6)
	v_permlane32_swap_b32_e32 v244, v246
	v_permlane32_swap_b32_e32 v245, v247
	v_lshlrev_b32_e32 v10, 16, v244
	v_mul_f32_e32 v0, v0, v10
	v_mul_f32_e32 v10, v57, v92
	v_and_b32_e32 v11, 0xffff0000, v244
	v_mul_f32_e32 v10, v10, v11
	v_cvt_pk_bf16_f32 v140, v0, v10
	v_mul_f32_e32 v0, v58, v92
	v_lshlrev_b32_e32 v11, 16, v245
	v_mfma_f32_32x32x16_bf16 v[32:47], v[104:107], v[188:191], v[32:47]
	v_mul_f32_e32 v0, v0, v11
	v_mul_f32_e32 v11, v59, v92
	v_and_b32_e32 v12, 0xffff0000, v245
	v_mul_f32_e32 v11, v11, v12
	v_cvt_pk_bf16_f32 v141, v0, v11
	v_mul_f32_e32 v0, v60, v92
	s_waitcnt vmcnt(6)
	v_lshlrev_b32_e32 v10, 16, v246
	v_mul_f32_e32 v0, v0, v10
	v_mul_f32_e32 v10, v61, v92
	v_and_b32_e32 v11, 0xffff0000, v246
	v_mul_f32_e32 v10, v10, v11
	v_cvt_pk_bf16_f32 v142, v0, v10
	v_mul_f32_e32 v0, v62, v92
	v_lshlrev_b32_e32 v11, 16, v247
	v_mul_f32_e32 v0, v0, v11
	v_mul_f32_e32 v11, v63, v92
	v_and_b32_e32 v12, 0xffff0000, v247
	v_mul_f32_e32 v11, v11, v12
	v_cvt_pk_bf16_f32 v143, v0, v11
	s_nop 1
	v_permlane32_swap_b32_e32 v140, v142
	v_permlane32_swap_b32_e32 v141, v143
	global_store_dwordx4 v[252:253], v[140:143], off offset:1120
	v_mul_f32_e32 v0, v32, v92
	s_waitcnt vmcnt(7)
	v_permlane32_swap_b32_e32 v248, v250
	v_permlane32_swap_b32_e32 v249, v251
	v_lshlrev_b32_e32 v10, 16, v248
	v_mul_f32_e32 v0, v0, v10
	v_mul_f32_e32 v10, v33, v92
	v_and_b32_e32 v11, 0xffff0000, v248
	v_mul_f32_e32 v10, v10, v11
	v_cvt_pk_bf16_f32 v136, v0, v10
	v_mul_f32_e32 v0, v34, v92
	v_lshlrev_b32_e32 v11, 16, v249
	v_mul_f32_e32 v0, v0, v11
	v_mul_f32_e32 v11, v35, v92
	v_and_b32_e32 v12, 0xffff0000, v249
	v_mul_f32_e32 v11, v11, v12
	v_cvt_pk_bf16_f32 v137, v0, v11
	v_mul_f32_e32 v0, v36, v92
	s_waitcnt vmcnt(7)
	v_lshlrev_b32_e32 v10, 16, v250
	v_mul_f32_e32 v0, v0, v10
	v_mul_f32_e32 v10, v37, v92
	v_and_b32_e32 v11, 0xffff0000, v250
	v_mfma_f32_32x32x16_bf16 v[16:31], v[112:115], v[192:195], v[16:31]
	v_mul_f32_e32 v10, v10, v11
	v_cvt_pk_bf16_f32 v138, v0, v10
	v_mul_f32_e32 v0, v38, v92
	v_lshlrev_b32_e32 v11, 16, v251
	v_mul_f32_e32 v0, v0, v11
	v_mul_f32_e32 v11, v39, v92
	v_and_b32_e32 v12, 0xffff0000, v251
	v_mul_f32_e32 v11, v11, v12
	v_cvt_pk_bf16_f32 v139, v0, v11
	s_nop 1
	v_permlane32_swap_b32_e32 v136, v138
	v_permlane32_swap_b32_e32 v137, v139
	global_store_dwordx4 v[252:253], v[136:139], off offset:1152
	v_mul_f32_e32 v0, v40, v92
	s_waitcnt vmcnt(7)
	v_permlane32_swap_b32_e32 v156, v158
	v_permlane32_swap_b32_e32 v157, v159
	v_lshlrev_b32_e32 v10, 16, v156
	v_mul_f32_e32 v0, v0, v10
	v_mul_f32_e32 v10, v41, v92
	v_and_b32_e32 v11, 0xffff0000, v156
	v_mul_f32_e32 v10, v10, v11
	v_cvt_pk_bf16_f32 v140, v0, v10
	v_mul_f32_e32 v0, v42, v92
	v_lshlrev_b32_e32 v11, 16, v157
	v_mfma_f32_32x32x16_bf16 v[16:31], v[116:119], v[188:191], v[16:31]
	v_mul_f32_e32 v0, v0, v11
	v_mul_f32_e32 v11, v43, v92
	v_and_b32_e32 v12, 0xffff0000, v157
	v_mul_f32_e32 v11, v11, v12
	v_cvt_pk_bf16_f32 v141, v0, v11
	v_mul_f32_e32 v0, v44, v92
	s_waitcnt vmcnt(7)
	v_lshlrev_b32_e32 v10, 16, v158
	v_mul_f32_e32 v0, v0, v10
	v_mul_f32_e32 v10, v45, v92
	v_and_b32_e32 v11, 0xffff0000, v158
	v_mul_f32_e32 v10, v10, v11
	v_cvt_pk_bf16_f32 v142, v0, v10
	v_mul_f32_e32 v0, v46, v92
	v_lshlrev_b32_e32 v11, 16, v159
	v_mul_f32_e32 v0, v0, v11
	v_mul_f32_e32 v11, v47, v92
	v_and_b32_e32 v12, 0xffff0000, v159
	v_mul_f32_e32 v11, v11, v12
	v_cvt_pk_bf16_f32 v143, v0, v11
	s_nop 1
	v_permlane32_swap_b32_e32 v140, v142
	v_permlane32_swap_b32_e32 v141, v143
	global_store_dwordx4 v[252:253], v[140:143], off offset:1184
	v_mul_f32_e32 v0, v16, v92
	s_waitcnt vmcnt(7)
	v_permlane32_swap_b32_e32 v160, v162
	v_permlane32_swap_b32_e32 v161, v163
	v_lshlrev_b32_e32 v10, 16, v160
	v_mul_f32_e32 v0, v0, v10
	v_mul_f32_e32 v10, v17, v92
	v_and_b32_e32 v11, 0xffff0000, v160
	v_mul_f32_e32 v10, v10, v11
	v_cvt_pk_bf16_f32 v136, v0, v10
	v_mul_f32_e32 v0, v18, v92
	v_lshlrev_b32_e32 v11, 16, v161
	v_mul_f32_e32 v0, v0, v11
	v_mul_f32_e32 v11, v19, v92
	v_and_b32_e32 v12, 0xffff0000, v161
	v_mul_f32_e32 v11, v11, v12
	v_cvt_pk_bf16_f32 v137, v0, v11
	v_mul_f32_e32 v0, v20, v92
	s_waitcnt vmcnt(7)
	v_lshlrev_b32_e32 v10, 16, v162
	v_mul_f32_e32 v0, v0, v10
	v_mul_f32_e32 v10, v21, v92
	v_and_b32_e32 v8, 0xffff0000, v162
	v_mul_f32_e32 v8, v10, v8
	v_cvt_pk_bf16_f32 v138, v0, v8
	v_mul_f32_e32 v0, v22, v92
	v_lshlrev_b32_e32 v10, 16, v163
	v_mul_f32_e32 v0, v0, v10
	v_mul_f32_e32 v10, v23, v92
	v_and_b32_e32 v9, 0xffff0000, v163
	v_mul_f32_e32 v9, v10, v9
	v_cvt_pk_bf16_f32 v139, v0, v9
	s_nop 1
	v_permlane32_swap_b32_e32 v136, v138
	v_permlane32_swap_b32_e32 v137, v139
	global_store_dwordx4 v[252:253], v[136:139], off offset:1216
	v_mul_f32_e32 v0, v24, v92
	s_waitcnt vmcnt(7)
	v_permlane32_swap_b32_e32 v164, v166
	v_permlane32_swap_b32_e32 v165, v167
	v_lshlrev_b32_e32 v8, 16, v164
	v_mul_f32_e32 v0, v0, v8
	v_mul_f32_e32 v8, v25, v92
	v_and_b32_e32 v4, 0xffff0000, v164
	v_mul_f32_e32 v4, v8, v4
	v_cvt_pk_bf16_f32 v140, v0, v4
	v_mul_f32_e32 v0, v26, v92
	v_lshlrev_b32_e32 v8, 16, v165
	v_mul_f32_e32 v0, v0, v8
	v_mul_f32_e32 v8, v27, v92
	v_and_b32_e32 v5, 0xffff0000, v165
	v_mul_f32_e32 v5, v8, v5
	v_cvt_pk_bf16_f32 v141, v0, v5
	v_mul_f32_e32 v0, v28, v92
	s_waitcnt vmcnt(7)
	v_lshlrev_b32_e32 v4, 16, v166
	v_mul_f32_e32 v0, v0, v4
	v_mul_f32_e32 v4, v29, v92
	v_and_b32_e32 v2, 0xffff0000, v166
	v_mul_f32_e32 v2, v4, v2
	v_cvt_pk_bf16_f32 v142, v0, v2
	v_mul_f32_e32 v0, v30, v92
	v_lshlrev_b32_e32 v4, 16, v167
	v_mul_f32_e32 v0, v0, v4
	v_mul_f32_e32 v4, v31, v92
	v_and_b32_e32 v3, 0xffff0000, v167
	v_mul_f32_e32 v3, v4, v3
	v_cvt_pk_bf16_f32 v143, v0, v3
	s_nop 1
	v_permlane32_swap_b32_e32 v140, v142
	v_permlane32_swap_b32_e32 v141, v143
	global_store_dwordx4 v[252:253], v[140:143], off offset:1248
	s_cbranch_scc0 .LBB0_1198

.LBB0_1189:
	v_add_u32_e32 v0, s57, v215
	ds_read_b128 v[2:5], v0
	ds_read_b128 v[6:9], v0 offset:32
	v_mov_b64_e32 v[110:111], v[94:95]
	v_mov_b64_e32 v[108:109], v[92:93]
	v_mov_b64_e32 v[106:107], v[90:91]
	s_waitcnt lgkmcnt(1)
	v_mfma_f32_32x32x16_bf16 v[112:127], v[2:5], v[128:131], v[80:95]
	ds_read_b128 v[2:5], v0 offset:12800
	ds_read_b128 v[10:13], v0 offset:12832
	v_mov_b64_e32 v[104:105], v[88:89]
	v_mov_b64_e32 v[102:103], v[86:87]
	v_mov_b64_e32 v[100:101], v[84:85]
	v_mov_b64_e32 v[98:99], v[82:83]
	v_mov_b64_e32 v[96:97], v[80:81]
	s_waitcnt lgkmcnt(2)
	v_mfma_f32_32x32x16_bf16 v[112:127], v[6:9], v[132:135], v[112:127]
	s_add_i32 s6, s36, 0xffffffa0
	s_lshl_b64 s[64:65], s[6:7], 1
	s_waitcnt lgkmcnt(1)
	v_mfma_f32_32x32x16_bf16 v[96:111], v[2:5], v[128:131], v[96:111]
	ds_read_b128 v[2:5], v0 offset:64
	ds_read_b128 v[6:9], v0 offset:96
	s_waitcnt lgkmcnt(2)
	v_mfma_f32_32x32x16_bf16 v[96:111], v[10:13], v[132:135], v[96:111]
	s_waitcnt lgkmcnt(1)
	v_mfma_f32_32x32x16_bf16 v[112:127], v[2:5], v[136:139], v[112:127]
	ds_read_b128 v[2:5], v0 offset:12864
	ds_read_b128 v[10:13], v0 offset:12896
	s_waitcnt lgkmcnt(1)
	v_mfma_f32_32x32x16_bf16 v[96:111], v[2:5], v[136:139], v[96:111]
	v_mfma_f32_32x32x16_bf16 v[112:127], v[6:9], v[140:143], v[112:127]
	ds_read_b128 v[2:5], v0 offset:128
	ds_read_b128 v[6:9], v0 offset:160
	s_waitcnt lgkmcnt(2)
	v_mfma_f32_32x32x16_bf16 v[96:111], v[10:13], v[140:143], v[96:111]
	s_waitcnt lgkmcnt(1)
	v_mfma_f32_32x32x16_bf16 v[112:127], v[2:5], v[144:147], v[112:127]
	ds_read_b128 v[2:5], v0 offset:12928
	ds_read_b128 v[10:13], v0 offset:12960
	s_waitcnt lgkmcnt(1)
	v_mfma_f32_32x32x16_bf16 v[96:111], v[2:5], v[144:147], v[96:111]
	v_mfma_f32_32x32x16_bf16 v[112:127], v[6:9], v[148:151], v[112:127]
	ds_read_b128 v[2:5], v0 offset:192
	ds_read_b128 v[6:9], v0 offset:224
	s_waitcnt lgkmcnt(2)
	v_mfma_f32_32x32x16_bf16 v[96:111], v[10:13], v[148:151], v[96:111]
	s_waitcnt lgkmcnt(1)
	v_mfma_f32_32x32x16_bf16 v[112:127], v[2:5], v[152:155], v[112:127]
	ds_read_b128 v[2:5], v0 offset:12992
	ds_read_b128 v[10:13], v0 offset:13024
	s_waitcnt lgkmcnt(1)
	v_mfma_f32_32x32x16_bf16 v[96:111], v[2:5], v[152:155], v[96:111]
	v_mfma_f32_32x32x16_bf16 v[112:127], v[6:9], v[156:159], v[112:127]
	ds_read_b128 v[2:5], v0 offset:256
	ds_read_b128 v[6:9], v0 offset:288
	s_waitcnt lgkmcnt(2)
	v_mfma_f32_32x32x16_bf16 v[96:111], v[10:13], v[156:159], v[96:111]
	s_waitcnt lgkmcnt(1)
	v_mfma_f32_32x32x16_bf16 v[112:127], v[2:5], v[160:163], v[112:127]
	ds_read_b128 v[2:5], v0 offset:13056
	ds_read_b128 v[10:13], v0 offset:13088
	s_waitcnt lgkmcnt(1)
	v_mfma_f32_32x32x16_bf16 v[96:111], v[2:5], v[160:163], v[96:111]
	v_mfma_f32_32x32x16_bf16 v[112:127], v[6:9], v[164:167], v[112:127]
	ds_read_b128 v[2:5], v0 offset:320
	ds_read_b128 v[6:9], v0 offset:352
	s_waitcnt lgkmcnt(2)
	v_mfma_f32_32x32x16_bf16 v[96:111], v[10:13], v[164:167], v[96:111]
	s_waitcnt lgkmcnt(1)
	v_mfma_f32_32x32x16_bf16 v[112:127], v[2:5], v[168:171], v[112:127]
	ds_read_b128 v[2:5], v0 offset:13120
	ds_read_b128 v[10:13], v0 offset:13152
	s_waitcnt lgkmcnt(1)
	v_mfma_f32_32x32x16_bf16 v[96:111], v[2:5], v[168:171], v[96:111]
	v_lshl_add_u64 v[2:3], v[206:207], 0, s[64:65]
	v_lshl_add_u64 v[4:5], v[218:219], 0, s[64:65]
	v_mfma_f32_32x32x16_bf16 v[112:127], v[6:9], v[172:175], v[112:127]
	s_and_b64 vcc, exec, s[38:39]
	s_cbranch_vccz .Llg_b
	global_load_dwordx4 v[156:159], v[252:253], off offset:160
	global_load_dwordx4 v[160:163], v[252:253], off offset:192
	global_load_dwordx4 v[164:167], v[252:253], off offset:224
.Llg_b:
	global_load_dwordx4 v[6:9], v[2:3], off
	s_nop 0
	global_load_dwordx4 v[2:5], v[4:5], off
	s_waitcnt lgkmcnt(0)
	v_mfma_f32_32x32x16_bf16 v[96:111], v[10:13], v[172:175], v[96:111]
	s_add_i32 s6, s62, 0
	s_add_i32 s6, s6, 0x12c00
	v_add_u32_e32 v0, s6, v227
	v_add_u32_e32 v220, v0, v226
	ds_read2_b64 v[10:13], v220 offset1:2
	v_add_u32_e32 v0, s36, v225
	v_add_u32_e32 v14, 0xffffffa0, v0
	v_subrev_u32_e32 v15, 64, v0
	v_cmp_le_i32_e32 vcc, v14, v216
	v_add_u32_e32 v221, 0x1000, v220
	ds_read2_b64 v[236:239], v221 offset0:32 offset1:34
	v_cndmask_b32_e32 v229, v224, v112, vcc
	v_cmp_le_i32_e32 vcc, v15, v216
	s_waitcnt lgkmcnt(1)
	v_mfma_f32_32x32x16_bf16 v[64:79], v[10:13], v[200:203], v[64:79]
	v_subrev_u32_e32 v11, 63, v0
	v_cndmask_b32_e32 v231, v224, v96, vcc
	v_cmp_lt_i32_e32 vcc, v14, v216
	v_add_u32_e32 v12, 0xffffffa2, v0
	v_max_f32_e32 v10, v229, v229
	v_cndmask_b32_e32 v233, v229, v112, vcc
	v_cndmask_b32_e32 v232, v224, v113, vcc
	v_cmp_le_i32_e32 vcc, v11, v216
	v_max_f32_e32 v10, 0xff800000, v10
	s_nop 0
	v_cndmask_b32_e32 v234, v224, v97, vcc
	v_cmp_le_i32_e32 vcc, v12, v216
	v_subrev_u32_e32 v12, 62, v0
	v_max3_f32 v11, v231, s52, v234
	v_cndmask_b32_e32 v14, v224, v114, vcc
	v_cmp_le_i32_e32 vcc, v12, v216
	s_nop 1
	v_cndmask_b32_e32 v96, v224, v98, vcc
	v_max3_f32 v98, v10, v232, v14
	v_add_u32_e32 v10, 0xffffffa3, v0
	v_cmp_le_i32_e32 vcc, v10, v216
	v_subrev_u32_e32 v10, 61, v0
	s_nop 0
	v_cndmask_b32_e32 v15, v224, v115, vcc
	v_cmp_le_i32_e32 vcc, v10, v216
	s_nop 1
	v_cndmask_b32_e32 v97, v224, v99, vcc
	v_max3_f32 v99, v11, v96, v97
	v_add_u32_e32 v112, 0xffffffa8, v0
	v_cmp_le_i32_e32 vcc, v112, v216
	v_subrev_u32_e32 v113, 56, v0
	s_waitcnt lgkmcnt(0)
	v_mfma_f32_32x32x16_bf16 v[48:63], v[236:239], v[200:203], v[48:63]
	v_cndmask_b32_e32 v112, v224, v116, vcc
	v_cmp_le_i32_e32 vcc, v113, v216
	v_max3_f32 v116, v98, v15, v112
	v_add_u32_e32 v98, 0xffffffa9, v0
	v_cndmask_b32_e32 v114, v224, v100, vcc
	v_cmp_le_i32_e32 vcc, v98, v216
	v_subrev_u32_e32 v98, 55, v0
	v_add_u32_e32 v229, 0x2000, v220
	v_cndmask_b32_e32 v113, v224, v117, vcc
	v_cmp_le_i32_e32 vcc, v98, v216
	v_add_u32_e32 v98, 0xffffffaa, v0
	ds_read2_b64 v[10:13], v229 offset0:64 offset1:66
	v_cndmask_b32_e32 v115, v224, v101, vcc
	v_max3_f32 v117, v99, v114, v115
	v_cmp_le_i32_e32 vcc, v98, v216
	v_subrev_u32_e32 v99, 54, v0
	v_subrev_u32_e32 v101, 53, v0
	v_cndmask_b32_e32 v98, v224, v118, vcc
	v_cmp_le_i32_e32 vcc, v99, v216
	v_add_u32_e32 v99, 0xffffffab, v0
	s_nop 0
	v_cndmask_b32_e32 v100, v224, v102, vcc
	v_cmp_le_i32_e32 vcc, v99, v216
	v_max3_f32 v102, v116, v113, v98
	s_nop 0
	v_cndmask_b32_e32 v99, v224, v119, vcc
	v_cmp_le_i32_e32 vcc, v101, v216
	s_nop 1
	v_cndmask_b32_e32 v101, v224, v103, vcc
	v_max3_f32 v103, v117, v100, v101
	v_add_u32_e32 v116, 0xffffffb0, v0
	v_cmp_le_i32_e32 vcc, v116, v216
	v_subrev_u32_e32 v117, 48, v0
	s_waitcnt lgkmcnt(0)
	v_mfma_f32_32x32x16_bf16 v[32:47], v[10:13], v[200:203], v[32:47]
	v_cndmask_b32_e32 v116, v224, v120, vcc
	v_cmp_le_i32_e32 vcc, v117, v216
	v_add_u32_e32 v11, 0xffffffb1, v0
	v_add_u32_e32 v12, 0xffffffb2, v0
	v_cndmask_b32_e32 v118, v224, v104, vcc
	v_cmp_le_i32_e32 vcc, v11, v216
	v_subrev_u32_e32 v11, 47, v0
	v_add_u32_e32 v230, 0x3000, v220
	v_cndmask_b32_e32 v117, v224, v121, vcc
	v_cmp_le_i32_e32 vcc, v11, v216
	v_max3_f32 v10, v102, v99, v116
	ds_read2_b64 v[236:239], v230 offset0:96 offset1:98
	v_cndmask_b32_e32 v119, v224, v105, vcc
	v_cmp_le_i32_e32 vcc, v12, v216
	v_subrev_u32_e32 v12, 46, v0
	v_max3_f32 v11, v103, v118, v119
	v_cndmask_b32_e32 v102, v224, v122, vcc
	v_cmp_le_i32_e32 vcc, v12, v216
	v_add_u32_e32 v12, 0xffffffb3, v0
	v_max3_f32 v10, v10, v117, v102
	v_cndmask_b32_e32 v104, v224, v106, vcc
	v_cmp_le_i32_e32 vcc, v12, v216
	v_subrev_u32_e32 v12, 45, v0
	s_nop 0
	v_cndmask_b32_e32 v103, v224, v123, vcc
	v_cmp_le_i32_e32 vcc, v12, v216
	s_nop 1
	v_cndmask_b32_e32 v105, v224, v107, vcc
	v_max3_f32 v11, v11, v104, v105
	v_add_u32_e32 v12, 0xffffffb8, v0
	v_cmp_le_i32_e32 vcc, v12, v216
	v_subrev_u32_e32 v12, 40, v0
	s_waitcnt lgkmcnt(0)
	v_mfma_f32_32x32x16_bf16 v[16:31], v[236:239], v[200:203], v[16:31]
	v_cndmask_b32_e32 v106, v224, v124, vcc
	v_cmp_le_i32_e32 vcc, v12, v216
	v_add_u32_e32 v12, 0xffffffb9, v0
	v_max3_f32 v10, v10, v103, v106
	v_cndmask_b32_e32 v108, v224, v108, vcc
	v_cmp_le_i32_e32 vcc, v12, v216
	v_subrev_u32_e32 v12, 39, v0
	ds_read2_b64 v[120:123], v220 offset0:4 offset1:6
	v_cndmask_b32_e32 v107, v224, v125, vcc
	v_cmp_le_i32_e32 vcc, v12, v216
	v_add_u32_e32 v12, 0xffffffba, v0
	s_nop 0
	v_cndmask_b32_e32 v109, v224, v109, vcc
	v_cmp_le_i32_e32 vcc, v12, v216
	v_subrev_u32_e32 v12, 38, v0
	v_max3_f32 v11, v11, v108, v109
	v_cndmask_b32_e32 v124, v224, v126, vcc
	v_cmp_le_i32_e32 vcc, v12, v216
	v_max3_f32 v126, v10, v107, v124
	v_add_u32_e32 v10, 0xffffffbb, v0
	v_cndmask_b32_e32 v125, v224, v110, vcc
	v_cmp_le_i32_e32 vcc, v10, v216
	v_subrev_u32_e32 v0, 37, v0
	s_nop 0
	v_cndmask_b32_e32 v110, v224, v127, vcc
	v_cmp_le_i32_e32 vcc, v0, v216
	s_nop 1
	v_cndmask_b32_e32 v111, v224, v111, vcc
	v_max3_f32 v0, v11, v125, v111
	v_max3_f32 v0, v126, v110, v0
	v_mov_b32_e32 v126, v0
	ds_read2_b64 v[10:13], v221 offset0:36 offset1:38
	s_waitcnt lgkmcnt(1)
	v_mfma_f32_32x32x16_bf16 v[64:79], v[120:123], v[196:199], v[64:79]
	v_permlane32_swap_b32_e32 v126, v0
	v_max_f32_e32 v120, v126, v126
	v_max_f32_e32 v0, v0, v120
	v_cmp_lt_f32_e32 vcc, s53, v0
	s_cbranch_vccz .LBB0_1191
	v_max_f32_e32 v0, v0, v0
	v_max_f32_e32 v0, 0, v0
	v_add_f32_e32 v217, v217, v0
	v_sub_f32_e32 v233, v233, v0
	v_sub_f32_e32 v232, v232, v0
	v_sub_f32_e32 v231, v231, v0
	v_sub_f32_e32 v234, v234, v0
	v_pk_add_f32 v[14:15], v[14:15], v[0:1] op_sel_hi:[1,0] neg_lo:[0,1] neg_hi:[0,1]
	v_pk_add_f32 v[96:97], v[96:97], v[0:1] op_sel_hi:[1,0] neg_lo:[0,1] neg_hi:[0,1]
	v_pk_add_f32 v[112:113], v[112:113], v[0:1] op_sel_hi:[1,0] neg_lo:[0,1] neg_hi:[0,1]
	v_pk_add_f32 v[114:115], v[114:115], v[0:1] op_sel_hi:[1,0] neg_lo:[0,1] neg_hi:[0,1]
	v_pk_add_f32 v[98:99], v[98:99], v[0:1] op_sel_hi:[1,0] neg_lo:[0,1] neg_hi:[0,1]
	v_pk_add_f32 v[100:101], v[100:101], v[0:1] op_sel_hi:[1,0] neg_lo:[0,1] neg_hi:[0,1]
	v_pk_add_f32 v[116:117], v[116:117], v[0:1] op_sel_hi:[1,0] neg_lo:[0,1] neg_hi:[0,1]
	v_pk_add_f32 v[118:119], v[118:119], v[0:1] op_sel_hi:[1,0] neg_lo:[0,1] neg_hi:[0,1]
	v_pk_add_f32 v[102:103], v[102:103], v[0:1] op_sel_hi:[1,0] neg_lo:[0,1] neg_hi:[0,1]
	v_pk_add_f32 v[104:105], v[104:105], v[0:1] op_sel_hi:[1,0] neg_lo:[0,1] neg_hi:[0,1]
	v_pk_add_f32 v[106:107], v[106:107], v[0:1] op_sel_hi:[1,0] neg_lo:[0,1] neg_hi:[0,1]
	v_pk_add_f32 v[108:109], v[108:109], v[0:1] op_sel_hi:[1,0] neg_lo:[0,1] neg_hi:[0,1]
	v_sub_f32_e32 v124, v124, v0
	v_sub_f32_e32 v125, v125, v0
	v_pk_add_f32 v[110:111], v[110:111], v[0:1] op_sel_hi:[1,0] neg_lo:[0,1] neg_hi:[0,1]
	v_exp_f32_e64 v0, -v0
	v_xor_b32_e32 v80, 0x80000000, v217
	v_mov_b32_e32 v81, v80
	v_mov_b32_e32 v82, v80
	v_mov_b32_e32 v83, v80
	v_mov_b32_e32 v84, v80
	v_mov_b32_e32 v85, v80
	v_mov_b32_e32 v86, v80
	v_mov_b32_e32 v87, v80
	v_mov_b32_e32 v88, v80
	v_mov_b32_e32 v89, v80
	v_mov_b32_e32 v90, v80
	v_mov_b32_e32 v91, v80
	v_mov_b32_e32 v92, v80
	v_mov_b32_e32 v93, v80
	v_mov_b32_e32 v94, v80
	v_mov_b32_e32 v95, v80
	s_branch .LBB0_1192
